# lever 4: s_setprio 1/0 around the dense MFMA clusters (QK^T head, PV) of the attention tile loops, on top of the de-serialised transposes
# baseline (speedup 1.0000x reference)
; #define LAS __attribute__((address_space(3)))
; template <bool ISA>
; __device__ __forceinline__ void attn_unit(LAS unsigned char* lds, const AttnArgs& T, int sc, int wave, int) {
;     ...
;             const unsigned voff = (unsigned)(((lane >> 3) * pitch + (((lane & 7) ^ ((lane >> 3) & 6)) * 8)) * 2);
; #pragma unroll
;             for (int i = 0; i < 8; ++i)
;                 __builtin_amdgcn_global_load_lds((const unsigned*)((const char*)(vp + (size_t)(8 * i) * pitch) + voff), (LAS unsigned*)(vst + i * 1024), 16, 0, 0);
;         }
;         bf16x8 pf[4][2];
; #pragma unroll
;         for (int qh = 0; qh < 2; ++qh) {
;             f32x4 s[4][2];
;             const LAS float* eb = ext + (768 + 32 * qh + fr - 64 * kc - 4 * fq);
; #pragma unroll
;             for (int kb = 0; kb < 4; ++kb)
; #pragma unroll
;                 for (int q2 = 0; q2 < 2; ++q2) {
;                     f32x4 c0 = (f32x4){0.f, 0.f, 0.f, 0.f};
;                     if (ISA) { const LAS float* e = eb + (16 * q2 - 16 * kb); c0 = (f32x4){e[0], e[-1], e[-2], e[-3]}; }
;                     f32x4 t = __builtin_amdgcn_mfma_f32_16x16x32_bf16(kf[kb][0], qf[2 * qh + q2][0], c0, 0, 0, 0);
;                     s[kb][q2] = __builtin_amdgcn_mfma_f32_16x16x32_bf16(kf[kb][1], qf[2 * qh + q2][1], t, 0, 0, 0);
;                 }
;             if (qh == 1) { const int kn = kc < NPREV ? kc + 1 : kc; const bf16 *kpn, *vpn; int pitchn; ATT_TILE_PTRS(kn, kpn, vpn, pitchn); (void)vpn; ATT_LOAD_K(kpn, pitchn); }
; #pragma unroll
;             for (int q2 = 0; q2 < 2; ++q2) {
;                 const int qb = 2 * qh + q2;
;                 float mx = fmaxf(fmaxf(s[0][q2][0], s[0][q2][1]), s[0][q2][2]);
;                 mx = fmaxf(fmaxf(mx, s[0][q2][3]), s[1][q2][0]); mx = fmaxf(fmaxf(mx, s[1][q2][1]), s[1][q2][2]); mx = fmaxf(fmaxf(mx, s[1][q2][3]), s[2][q2][0]);
;                 mx = fmaxf(fmaxf(mx, s[2][q2][1]), s[2][q2][2]); mx = fmaxf(fmaxf(mx, s[2][q2][3]), s[3][q2][0]); mx = fmaxf(fmaxf(mx, s[3][q2][1]), s[3][q2][2]); mx = fmaxf(mx, s[3][q2][3]);
;                 if (!__all(mx <= mrow[qb] + ATT_THR)) {
;                     mx = fmaxf(mx, __shfl_xor(mx, 16)); mx = fmaxf(mx, __shfl_xor(mx, 32));
;                     const float mnew = fmaxf(mrow[qb], mx), alpha = fexp2(mrow[qb] - mnew);
;                     mrow[qb] = mnew; lrow[qb] = lrow[qb] * alpha;
; #pragma unroll
.LBB0_360:
	v_mul_lo_u32 v0, v202, s36
	v_or_b32_e32 v0, v0, v201
	v_lshl_add_u64 v[2:3], s[58:59], 0, v[0:1]
	s_mov_b32 m0, s92
	s_lshl_b32 s10, s36, 4
	global_load_lds_dwordx4 v0, s[58:59]
	v_lshl_add_u64 v[132:133], v[2:3], 0, s[10:11]
	s_mov_b32 m0, s95
	s_lshl_b32 s10, s36, 5
	global_load_lds_dwordx4 v[132:133], off
	v_lshl_add_u64 v[132:133], v[2:3], 0, s[10:11]
	s_mov_b32 m0, s96
	s_mul_i32 s10, s36, 48
	global_load_lds_dwordx4 v[132:133], off
	v_lshl_add_u64 v[132:133], v[2:3], 0, s[10:11]
	s_mov_b32 m0, s97
	s_lshl_b32 s10, s36, 6
	global_load_lds_dwordx4 v[132:133], off
	v_lshl_add_u64 v[132:133], v[2:3], 0, s[10:11]
	s_mov_b32 m0, s91
	s_mul_i32 s10, s36, 0x50
	global_load_lds_dwordx4 v[132:133], off
	v_lshl_add_u64 v[132:133], v[2:3], 0, s[10:11]
	s_mov_b32 m0, s72
	s_mul_i32 s10, s36, 0x60
	global_load_lds_dwordx4 v[132:133], off
	v_lshl_add_u64 v[132:133], v[2:3], 0, s[10:11]
	s_mov_b32 m0, s73
	s_mul_i32 s10, s36, 0x70
	global_load_lds_dwordx4 v[132:133], off
	v_lshl_add_u64 v[2:3], v[2:3], 0, s[10:11]
	s_mov_b32 m0, s4
	s_waitcnt vmcnt(7)
	s_setprio 1
	v_mfma_f32_16x16x32_bf16 v[132:135], v[64:67], v[4:7], 0
	global_load_lds_dwordx4 v[2:3], off
	v_mfma_f32_16x16x32_bf16 v[140:143], v[56:59], v[4:7], 0
	v_mfma_f32_16x16x32_bf16 v[132:135], v[60:63], v[8:11], v[132:135]
	v_mfma_f32_16x16x32_bf16 v[148:151], v[48:51], v[4:7], 0
	v_mfma_f32_16x16x32_bf16 v[140:143], v[52:55], v[8:11], v[140:143]
	s_nop 5
	v_max_f32_e32 v0, v133, v133
	v_max_f32_e32 v2, v132, v132
	v_max_f32_e32 v0, v2, v0
	v_mfma_f32_16x16x32_bf16 v[152:155], v[40:43], v[4:7], 0
	v_max3_f32 v0, v0, v134, v135
	v_max3_f32 v0, v0, v140, v141
	v_max3_f32 v0, v0, v142, v143
	v_mfma_f32_16x16x32_bf16 v[156:159], v[44:47], v[8:11], v[148:151]
	v_add_f32_e32 v2, 0x40c00000, v208
	v_mfma_f32_16x16x32_bf16 v[136:139], v[64:67], v[12:15], 0
	v_mfma_f32_16x16x32_bf16 v[144:147], v[56:59], v[12:15], 0
	s_nop 4
	v_max3_f32 v0, v0, v156, v157
	v_max3_f32 v0, v0, v158, v159
	v_mfma_f32_16x16x32_bf16 v[148:151], v[48:51], v[12:15], 0
	v_mfma_f32_16x16x32_bf16 v[160:163], v[36:39], v[8:11], v[152:155]
	v_mfma_f32_16x16x32_bf16 v[152:155], v[40:43], v[12:15], 0
	v_mfma_f32_16x16x32_bf16 v[136:139], v[60:63], v[16:19], v[136:139]
	s_nop 5
	v_max3_f32 v0, v0, v160, v161
	v_max3_f32 v0, v0, v162, v163
	v_cmp_le_f32_e32 vcc, v0, v2
	v_mfma_f32_16x16x32_bf16 v[144:147], v[52:55], v[16:19], v[144:147]
	s_cmp_eq_u64 vcc, exec
	v_mfma_f32_16x16x32_bf16 v[148:151], v[44:47], v[16:19], v[148:151]
	v_mfma_f32_16x16x32_bf16 v[152:155], v[36:39], v[16:19], v[152:155]
	s_setprio 0
	s_cbranch_scc1 .LBB0_362
	ds_bpermute_b32 v2, v197, v0
	v_max_f32_e32 v0, v0, v0
	s_waitcnt lgkmcnt(0)
	v_max_f32_e32 v2, v2, v2
	v_max_f32_e32 v0, v0, v2
	ds_bpermute_b32 v2, v198, v0
	s_waitcnt lgkmcnt(0)
	v_max3_f32 v2, v208, v0, v2
	v_sub_f32_e32 v0, v208, v2
	v_exp_f32_e32 v0, v0
	v_mov_b32_e32 v208, v2
	v_mul_f32_e32 v207, v207, v0
	v_pk_mul_f32 v[118:119], v[118:119], v[0:1] op_sel_hi:[1,0]
	v_pk_mul_f32 v[116:117], v[116:117], v[0:1] op_sel_hi:[1,0]
	v_pk_mul_f32 v[122:123], v[122:123], v[0:1] op_sel_hi:[1,0]
	v_pk_mul_f32 v[120:121], v[120:121], v[0:1] op_sel_hi:[1,0]
	v_pk_mul_f32 v[130:131], v[130:131], v[0:1] op_sel_hi:[1,0]
	v_pk_mul_f32 v[128:129], v[128:129], v[0:1] op_sel_hi:[1,0]
	v_pk_mul_f32 v[126:127], v[126:127], v[0:1] op_sel_hi:[1,0]
	v_pk_mul_f32 v[124:125], v[124:125], v[0:1] op_sel_hi:[1,0]

; #define LAS __attribute__((address_space(3)))
; __device__ __forceinline__ unsigned cvt_pk(float lo, float hi) { unsigned r; asm("v_cvt_pk_bf16_f32 %0, %1, %2" : "=v"(r) : "v"(lo), "v"(hi)); return r; }
; __device__ __forceinline__ float fexp2(float x) { return __builtin_amdgcn_exp2f(x); }
; template <bool ISA>
; __device__ __forceinline__ void attn_unit(LAS unsigned char* lds, const AttnArgs& T, int sc, int wave, int) {
;     ...
;                 const float mcur = mrow[qb];
;                 float ps = 0.f; float p[4][4];
; #pragma unroll
;                 for (int kb = 0; kb < 4; ++kb)
; #pragma unroll
;                     for (int j = 0; j < 4; ++j) { p[kb][j] = fexp2(s[kb][q2][j] - mcur); ps += p[kb][j]; }
;                 lrow[qb] += ps;
; #pragma unroll
;                 for (int kp2 = 0; kp2 < 2; ++kp2) {
;                     v4u w; w.x = cvt_pk(p[2 * kp2][0], p[2 * kp2][1]); w.y = cvt_pk(p[2 * kp2][2], p[2 * kp2][3]);
;                     w.z = cvt_pk(p[2 * kp2 + 1][0], p[2 * kp2 + 1][1]); w.w = cvt_pk(p[2 * kp2 + 1][2], p[2 * kp2 + 1][3]);
;                     pf[qb][kp2] = __builtin_bit_cast(bf16x8, w);
;                 }
;             }
;         }
;         asm volatile("s_waitcnt vmcnt(8)" ::: "memory");
;         __builtin_amdgcn_wave_barrier();
;         const int tq = (lane & 15) >> 2, tp = lane & 3;
; #pragma unroll
;         for (int kp2 = 0; kp2 < 2; ++kp2) {
;             bf16x8 vf[4];
; #pragma unroll
;             for (int db = 0; db < 4; ++db) {
;                 const int r8 = 4 * (fq & 1) + tq;
;                 LAS unsigned char* a0 = vst + (4 * kp2 + (fq >> 1)) * 1024 + r8 * 128 + (((2 * db + (tp >> 1)) ^ (r8 & 6)) * 16) + (tp & 1) * 8;
;                 const s16x4 lo = __builtin_bit_cast(s16x4, __builtin_amdgcn_ds_read_tr16_b64_v4i16((LAS s16x4*)a0));
;                 const s16x4 hi = __builtin_bit_cast(s16x4, __builtin_amdgcn_ds_read_tr16_b64_v4i16((LAS s16x4*)(a0 + 2048)));
;                 vf[db] = (bf16x8){lo[0], lo[1], lo[2], lo[3], hi[0], hi[1], hi[2], hi[3]};
;             }
; #pragma unroll
;             for (int qb = 0; qb < 4; ++qb)
; #pragma unroll
;                 for (int db = 0; db < 4; ++db) o[db][qb] = __builtin_amdgcn_mfma_f32_16x16x32_bf16(vf[db], pf[qb][kp2], o[db][qb], 0, 0, 0);
;         }
.LBB0_368:
	v_add_f32_e32 v0, 0, v0
	v_add_f32_e32 v0, v239, v0
	v_add_f32_e32 v0, v240, v0
	v_add_f32_e32 v0, v241, v0
	v_add_f32_e32 v0, v242, v0
	v_add_f32_e32 v0, v243, v0
	v_add_f32_e32 v0, v244, v0
	v_add_f32_e32 v0, v245, v0
	v_add_f32_e32 v0, v172, v0
	v_add_f32_e32 v0, v173, v0
	v_add_f32_e32 v0, v174, v0
	v_add_f32_e32 v0, v175, v0
	v_add_f32_e32 v0, v176, v0
	v_add_f32_e32 v0, v177, v0
	v_add_f32_e32 v0, v178, v0
	v_add_f32_e32 v0, v179, v0
	v_add_f32_e32 v193, v193, v0
	v_add_f32_e32 v0, 0, v223
	v_add_f32_e32 v0, v224, v0
	v_add_f32_e32 v0, v225, v0
	v_add_f32_e32 v0, v226, v0
	v_add_f32_e32 v0, v227, v0
	v_add_f32_e32 v0, v228, v0
	v_add_f32_e32 v0, v229, v0
	v_add_f32_e32 v0, v230, v0
	v_add_f32_e32 v0, v231, v0
	v_add_f32_e32 v0, v232, v0
	v_add_f32_e32 v0, v233, v0
	v_add_f32_e32 v0, v234, v0
	v_add_f32_e32 v0, v235, v0
	v_add_f32_e32 v0, v236, v0
	v_add_f32_e32 v0, v237, v0
	v_add_f32_e32 v0, v238, v0
	v_add_f32_e32 v195, v195, v0
	v_add_f32_e32 v0, 0, v2
	v_add_f32_e32 v0, v3, v0
	v_add_f32_e32 v0, v209, v0
	v_add_f32_e32 v0, v210, v0
	v_add_f32_e32 v0, v211, v0
	v_add_f32_e32 v0, v212, v0
	v_add_f32_e32 v0, v213, v0
	v_add_f32_e32 v0, v214, v0
	v_add_f32_e32 v0, v215, v0
	v_add_f32_e32 v0, v216, v0
	v_add_f32_e32 v0, v217, v0
	v_add_f32_e32 v0, v218, v0
	v_add_f32_e32 v0, v219, v0
	v_add_f32_e32 v0, v220, v0
	v_add_f32_e32 v0, v221, v0
	v_add_f32_e32 v0, v222, v0
	v_add_f32_e32 v207, v207, v0
	v_sub_f32_e32 v0, v152, v191
	v_exp_f32_e32 v0, v0
	v_sub_f32_e32 v3, v153, v191
	v_exp_f32_e32 v3, v3
	v_sub_f32_e32 v152, v154, v191
	v_exp_f32_e32 v152, v152
	v_sub_f32_e32 v153, v155, v191
	v_exp_f32_e32 v153, v153
	v_sub_f32_e32 v154, v160, v191
	v_add_f32_e32 v2, 0, v0
	v_exp_f32_e32 v154, v154
	v_sub_f32_e32 v155, v161, v191
	v_add_f32_e32 v2, v3, v2
	v_exp_f32_e32 v155, v155
	v_sub_f32_e32 v160, v162, v191
	v_add_f32_e32 v2, v152, v2
	v_exp_f32_e32 v172, v160
	v_sub_f32_e32 v160, v163, v191
	v_add_f32_e32 v2, v153, v2
	v_exp_f32_e32 v163, v160
	v_sub_f32_e32 v160, v168, v191
	v_add_f32_e32 v2, v154, v2
	v_exp_f32_e32 v168, v160
	v_sub_f32_e32 v160, v169, v191
	v_add_f32_e32 v2, v155, v2
	v_exp_f32_e32 v169, v160
	v_sub_f32_e32 v160, v170, v191
	v_add_f32_e32 v2, v172, v2
	v_exp_f32_e32 v170, v160
	v_sub_f32_e32 v160, v171, v191
	v_add_f32_e32 v2, v163, v2
	v_exp_f32_e32 v171, v160
	v_sub_f32_e32 v160, v164, v191
	v_add_f32_e32 v2, v168, v2
	v_exp_f32_e32 v164, v160
	v_sub_f32_e32 v160, v165, v191
	v_add_f32_e32 v2, v169, v2
	v_exp_f32_e32 v165, v160
	v_sub_f32_e32 v160, v166, v191
	v_add_f32_e32 v2, v170, v2
	v_exp_f32_e32 v166, v160
	v_sub_f32_e32 v160, v167, v191
	v_add_f32_e32 v2, v171, v2
	v_exp_f32_e32 v167, v160
	v_add_f32_e32 v2, v164, v2
	v_add_f32_e32 v2, v165, v2
	v_add_f32_e32 v2, v166, v2
	v_add_f32_e32 v2, v167, v2
	v_cvt_pk_bf16_f32 v161, v152, v153
	v_cvt_pk_bf16_f32 v162, v154, v155
	v_cvt_pk_bf16_f32 v163, v172, v163
	v_cvt_pk_bf16_f32 v152, v168, v169
	v_cvt_pk_bf16_f32 v153, v170, v171
	v_cvt_pk_bf16_f32 v154, v164, v165
	v_cvt_pk_bf16_f32 v155, v166, v167
	s_waitcnt vmcnt(8)
	ds_read_b64_tr_b16 v[164:165], v203
	ds_read_b64_tr_b16 v[166:167], v203 offset:2048
	ds_read_b64_tr_b16 v[168:169], v204
	ds_read_b64_tr_b16 v[170:171], v204 offset:2048
	ds_read_b64_tr_b16 v[172:173], v205
	ds_read_b64_tr_b16 v[174:175], v205 offset:2048
	ds_read_b64_tr_b16 v[176:177], v206
	ds_read_b64_tr_b16 v[178:179], v206 offset:2048
	v_cvt_pk_bf16_f32 v160, v0, v3
	s_waitcnt lgkmcnt(0)
	s_setprio 1
	v_mfma_f32_16x16x32_bf16 v[116:119], v[164:167], v[140:143], v[116:119]
	s_add_i32 s90, s90, 64
	v_add_f32_e32 v190, v190, v2
	s_cmp_gt_u32 s88, 1
	v_mfma_f32_16x16x32_bf16 v[120:123], v[168:171], v[140:143], v[120:123]
	v_mfma_f32_16x16x32_bf16 v[128:131], v[172:175], v[140:143], v[128:131]
	v_mfma_f32_16x16x32_bf16 v[124:127], v[176:179], v[140:143], v[124:127]
	v_mfma_f32_16x16x32_bf16 v[100:103], v[164:167], v[144:147], v[100:103]
	v_mfma_f32_16x16x32_bf16 v[104:107], v[168:171], v[144:147], v[104:107]
	v_mfma_f32_16x16x32_bf16 v[112:115], v[172:175], v[144:147], v[112:115]
	v_mfma_f32_16x16x32_bf16 v[108:111], v[176:179], v[144:147], v[108:111]
	v_mfma_f32_16x16x32_bf16 v[84:87], v[164:167], v[156:159], v[84:87]
	v_mfma_f32_16x16x32_bf16 v[88:91], v[168:171], v[156:159], v[88:91]
	v_mfma_f32_16x16x32_bf16 v[96:99], v[172:175], v[156:159], v[96:99]
	v_mfma_f32_16x16x32_bf16 v[92:95], v[176:179], v[156:159], v[92:95]
	v_mfma_f32_16x16x32_bf16 v[68:71], v[164:167], v[160:163], v[68:71]
	v_mfma_f32_16x16x32_bf16 v[72:75], v[168:171], v[160:163], v[72:75]
	v_mfma_f32_16x16x32_bf16 v[80:83], v[172:175], v[160:163], v[80:83]
	v_mfma_f32_16x16x32_bf16 v[76:79], v[176:179], v[160:163], v[76:79]
	ds_read_b64_tr_b16 v[144:145], v203 offset:4096
	ds_read_b64_tr_b16 v[146:147], v203 offset:6144
	ds_read_b64_tr_b16 v[160:161], v204 offset:4096
	ds_read_b64_tr_b16 v[162:163], v204 offset:6144
	ds_read_b64_tr_b16 v[156:157], v205 offset:4096
	ds_read_b64_tr_b16 v[158:159], v205 offset:6144
	ds_read_b64_tr_b16 v[140:141], v206 offset:4096
	ds_read_b64_tr_b16 v[142:143], v206 offset:6144
	s_waitcnt lgkmcnt(6)
	v_mfma_f32_16x16x32_bf16 v[116:119], v[144:147], v[132:135], v[116:119]
	s_waitcnt lgkmcnt(4)
	v_mfma_f32_16x16x32_bf16 v[120:123], v[160:163], v[132:135], v[120:123]
	s_waitcnt lgkmcnt(2)
	v_mfma_f32_16x16x32_bf16 v[128:131], v[156:159], v[132:135], v[128:131]
	s_waitcnt lgkmcnt(0)
	v_mfma_f32_16x16x32_bf16 v[124:127], v[140:143], v[132:135], v[124:127]
	v_mfma_f32_16x16x32_bf16 v[100:103], v[144:147], v[136:139], v[100:103]
	v_mfma_f32_16x16x32_bf16 v[104:107], v[160:163], v[136:139], v[104:107]
	v_mfma_f32_16x16x32_bf16 v[112:115], v[156:159], v[136:139], v[112:115]
	v_mfma_f32_16x16x32_bf16 v[108:111], v[140:143], v[136:139], v[108:111]
	v_mfma_f32_16x16x32_bf16 v[84:87], v[144:147], v[148:151], v[84:87]
	v_mfma_f32_16x16x32_bf16 v[88:91], v[160:163], v[148:151], v[88:91]
	v_mfma_f32_16x16x32_bf16 v[96:99], v[156:159], v[148:151], v[96:99]
	v_mfma_f32_16x16x32_bf16 v[92:95], v[140:143], v[148:151], v[92:95]
	v_mfma_f32_16x16x32_bf16 v[68:71], v[144:147], v[152:155], v[68:71]
	v_mfma_f32_16x16x32_bf16 v[72:75], v[160:163], v[152:155], v[72:75]
	v_mfma_f32_16x16x32_bf16 v[80:83], v[156:159], v[152:155], v[80:83]
	v_mfma_f32_16x16x32_bf16 v[76:79], v[140:143], v[152:155], v[76:79]
	s_setprio 0
	s_cbranch_scc1 .LBB0_371
	s_mov_b32 s88, s36
	s_branch .LBB0_356

; #define LAS __attribute__((address_space(3)))
; __device__ __forceinline__ unsigned cvt_pk(float lo, float hi) { unsigned r; asm("v_cvt_pk_bf16_f32 %0, %1, %2" : "=v"(r) : "v"(lo), "v"(hi)); return r; }
; __device__ __forceinline__ float fexp2(float x) { return __builtin_amdgcn_exp2f(x); }
; template <bool ISA>
; __device__ __forceinline__ void attn_unit(LAS unsigned char* lds, const AttnArgs& T, int sc, int wave, int) {
;     ...
;                 const float mcur = mrow[qb];
;                 float ps = 0.f; float p[4][4];
; #pragma unroll
;                 for (int kb = 0; kb < 4; ++kb)
; #pragma unroll
;                     for (int j = 0; j < 4; ++j) { p[kb][j] = fexp2(s[kb][q2][j] - mcur); ps += p[kb][j]; }
;                 lrow[qb] += ps;
; #pragma unroll
;                 for (int kp2 = 0; kp2 < 2; ++kp2) {
;                     v4u w; w.x = cvt_pk(p[2 * kp2][0], p[2 * kp2][1]); w.y = cvt_pk(p[2 * kp2][2], p[2 * kp2][3]);
;                     w.z = cvt_pk(p[2 * kp2 + 1][0], p[2 * kp2 + 1][1]); w.w = cvt_pk(p[2 * kp2 + 1][2], p[2 * kp2 + 1][3]);
;                     pf[qb][kp2] = __builtin_bit_cast(bf16x8, w);
;                 }
;             }
;         }
;         asm volatile("s_waitcnt vmcnt(8)" ::: "memory");
;         __builtin_amdgcn_wave_barrier();
;         const int tq = (lane & 15) >> 2, tp = lane & 3;
; #pragma unroll
;         for (int kp2 = 0; kp2 < 2; ++kp2) {
;             bf16x8 vf[4];
; #pragma unroll
;             for (int db = 0; db < 4; ++db) {
;                 const int r8 = 4 * (fq & 1) + tq;
;                 LAS unsigned char* a0 = vst + (4 * kp2 + (fq >> 1)) * 1024 + r8 * 128 + (((2 * db + (tp >> 1)) ^ (r8 & 6)) * 16) + (tp & 1) * 8;
;                 const s16x4 lo = __builtin_bit_cast(s16x4, __builtin_amdgcn_ds_read_tr16_b64_v4i16((LAS s16x4*)a0));
;                 const s16x4 hi = __builtin_bit_cast(s16x4, __builtin_amdgcn_ds_read_tr16_b64_v4i16((LAS s16x4*)(a0 + 2048)));
;                 vf[db] = (bf16x8){lo[0], lo[1], lo[2], lo[3], hi[0], hi[1], hi[2], hi[3]};
;             }
; #pragma unroll
;             for (int qb = 0; qb < 4; ++qb)
; #pragma unroll
;                 for (int db = 0; db < 4; ++db) o[db][qb] = __builtin_amdgcn_mfma_f32_16x16x32_bf16(vf[db], pf[qb][kp2], o[db][qb], 0, 0, 0);
;         }
.LBB0_402:
	v_add_f32_e32 v0, 0, v0
	v_add_f32_e32 v0, v172, v0
	v_add_f32_e32 v0, v173, v0
	v_add_f32_e32 v0, v174, v0
	v_add_f32_e32 v0, v175, v0
	v_add_f32_e32 v0, v176, v0
	v_add_f32_e32 v0, v177, v0
	v_add_f32_e32 v0, v178, v0
	v_add_f32_e32 v0, v179, v0
	v_add_f32_e32 v0, v180, v0
	v_add_f32_e32 v0, v181, v0
	v_add_f32_e32 v0, v182, v0
	v_add_f32_e32 v0, v183, v0
	v_add_f32_e32 v0, v243, v0
	v_add_f32_e32 v0, v244, v0
	v_add_f32_e32 v0, v245, v0
	v_add_f32_e32 v195, v195, v0
	v_add_f32_e32 v0, 0, v227
	v_add_f32_e32 v0, v228, v0
	v_add_f32_e32 v0, v229, v0
	v_add_f32_e32 v0, v230, v0
	v_add_f32_e32 v0, v231, v0
	v_add_f32_e32 v0, v232, v0
	v_add_f32_e32 v0, v233, v0
	v_add_f32_e32 v0, v234, v0
	v_add_f32_e32 v0, v235, v0
	v_add_f32_e32 v0, v236, v0
	v_add_f32_e32 v0, v237, v0
	v_add_f32_e32 v0, v238, v0
	v_add_f32_e32 v0, v239, v0
	v_add_f32_e32 v0, v240, v0
	v_add_f32_e32 v0, v241, v0
	v_add_f32_e32 v0, v242, v0
	v_add_f32_e32 v199, v199, v0
	v_add_f32_e32 v0, 0, v2
	v_add_f32_e32 v0, v3, v0
	v_add_f32_e32 v0, v213, v0
	v_add_f32_e32 v0, v214, v0
	v_add_f32_e32 v0, v215, v0
	v_add_f32_e32 v0, v216, v0
	v_add_f32_e32 v0, v217, v0
	v_add_f32_e32 v0, v218, v0
	v_add_f32_e32 v0, v219, v0
	v_add_f32_e32 v0, v220, v0
	v_add_f32_e32 v0, v221, v0
	v_add_f32_e32 v0, v222, v0
	v_add_f32_e32 v0, v223, v0
	v_add_f32_e32 v0, v224, v0
	v_add_f32_e32 v0, v225, v0
	v_add_f32_e32 v0, v226, v0
	v_add_f32_e32 v208, v208, v0
	v_sub_f32_e32 v0, v160, v209
	v_exp_f32_e32 v0, v0
	v_sub_f32_e32 v3, v161, v209
	v_exp_f32_e32 v3, v3
	v_sub_f32_e32 v160, v162, v209
	v_exp_f32_e32 v161, v160
	v_sub_f32_e32 v160, v163, v209
	v_exp_f32_e32 v162, v160
	v_sub_f32_e32 v160, v164, v209
	v_add_f32_e32 v2, 0, v0
	v_exp_f32_e32 v163, v160
	v_sub_f32_e32 v160, v165, v209
	v_add_f32_e32 v2, v3, v2
	v_exp_f32_e32 v164, v160
	v_sub_f32_e32 v160, v166, v209
	v_add_f32_e32 v2, v161, v2
	v_exp_f32_e32 v165, v160
	v_sub_f32_e32 v160, v167, v209
	v_add_f32_e32 v2, v162, v2
	v_exp_f32_e32 v166, v160
	v_sub_f32_e32 v160, v168, v209
	v_add_f32_e32 v2, v163, v2
	v_exp_f32_e32 v167, v160
	v_sub_f32_e32 v160, v169, v209
	v_add_f32_e32 v2, v164, v2
	v_exp_f32_e32 v168, v160
	v_sub_f32_e32 v160, v170, v209
	v_add_f32_e32 v2, v165, v2
	v_exp_f32_e32 v169, v160
	v_sub_f32_e32 v160, v171, v209
	v_add_f32_e32 v2, v166, v2
	v_exp_f32_e32 v170, v160
	v_sub_f32_e32 v152, v152, v209
	v_add_f32_e32 v2, v167, v2
	v_exp_f32_e32 v171, v152
	v_sub_f32_e32 v152, v153, v209
	v_add_f32_e32 v2, v168, v2
	v_exp_f32_e32 v172, v152
	v_sub_f32_e32 v152, v154, v209
	v_add_f32_e32 v2, v169, v2
	v_exp_f32_e32 v173, v152
	v_sub_f32_e32 v152, v155, v209
	v_add_f32_e32 v2, v170, v2
	v_exp_f32_e32 v155, v152
	v_add_f32_e32 v2, v171, v2
	v_add_f32_e32 v2, v172, v2
	v_add_f32_e32 v2, v173, v2
	v_add_f32_e32 v2, v155, v2
	v_cvt_pk_bf16_f32 v161, v161, v162
	v_cvt_pk_bf16_f32 v162, v163, v164
	v_cvt_pk_bf16_f32 v163, v165, v166
	v_cvt_pk_bf16_f32 v152, v167, v168
	v_cvt_pk_bf16_f32 v153, v169, v170
	v_cvt_pk_bf16_f32 v154, v171, v172
	v_cvt_pk_bf16_f32 v155, v173, v155
	s_waitcnt vmcnt(8)
	ds_read_b64_tr_b16 v[164:165], v204
	ds_read_b64_tr_b16 v[166:167], v204 offset:2048
	ds_read_b64_tr_b16 v[168:169], v205
	ds_read_b64_tr_b16 v[170:171], v205 offset:2048
	ds_read_b64_tr_b16 v[172:173], v206
	ds_read_b64_tr_b16 v[174:175], v206 offset:2048
	ds_read_b64_tr_b16 v[176:177], v207
	ds_read_b64_tr_b16 v[178:179], v207 offset:2048
	v_cvt_pk_bf16_f32 v160, v0, v3
	s_waitcnt lgkmcnt(6)
	s_setprio 1
	v_mfma_f32_16x16x32_bf16 v[116:119], v[164:167], v[140:143], v[116:119]
	s_addk_i32 s94, 0xff00
	s_add_i32 s90, s90, 64
	s_add_i32 s56, s56, 64
	s_waitcnt lgkmcnt(4)
	v_mfma_f32_16x16x32_bf16 v[124:127], v[168:171], v[140:143], v[124:127]
	v_add_f32_e32 v193, v193, v2
	s_cmp_gt_u32 s88, 7
	s_waitcnt lgkmcnt(2)
	v_mfma_f32_16x16x32_bf16 v[128:131], v[172:175], v[140:143], v[128:131]
	s_waitcnt lgkmcnt(0)
	v_mfma_f32_16x16x32_bf16 v[120:123], v[176:179], v[140:143], v[120:123]
	v_mfma_f32_16x16x32_bf16 v[100:103], v[164:167], v[144:147], v[100:103]
	v_mfma_f32_16x16x32_bf16 v[108:111], v[168:171], v[144:147], v[108:111]
	v_mfma_f32_16x16x32_bf16 v[112:115], v[172:175], v[144:147], v[112:115]
	v_mfma_f32_16x16x32_bf16 v[104:107], v[176:179], v[144:147], v[104:107]
	v_mfma_f32_16x16x32_bf16 v[84:87], v[164:167], v[156:159], v[84:87]
	v_mfma_f32_16x16x32_bf16 v[92:95], v[168:171], v[156:159], v[92:95]
	v_mfma_f32_16x16x32_bf16 v[96:99], v[172:175], v[156:159], v[96:99]
	v_mfma_f32_16x16x32_bf16 v[88:91], v[176:179], v[156:159], v[88:91]
	v_mfma_f32_16x16x32_bf16 v[68:71], v[164:167], v[160:163], v[68:71]
	v_mfma_f32_16x16x32_bf16 v[76:79], v[168:171], v[160:163], v[76:79]
	v_mfma_f32_16x16x32_bf16 v[80:83], v[172:175], v[160:163], v[80:83]
	v_mfma_f32_16x16x32_bf16 v[72:75], v[176:179], v[160:163], v[72:75]
	ds_read_b64_tr_b16 v[144:145], v204 offset:4096
	ds_read_b64_tr_b16 v[146:147], v204 offset:6144
	ds_read_b64_tr_b16 v[160:161], v205 offset:4096
	ds_read_b64_tr_b16 v[162:163], v205 offset:6144
	ds_read_b64_tr_b16 v[156:157], v206 offset:4096
	ds_read_b64_tr_b16 v[158:159], v206 offset:6144
	ds_read_b64_tr_b16 v[140:141], v207 offset:4096
	ds_read_b64_tr_b16 v[142:143], v207 offset:6144
	s_waitcnt lgkmcnt(6)
	v_mfma_f32_16x16x32_bf16 v[116:119], v[144:147], v[132:135], v[116:119]
	s_waitcnt lgkmcnt(4)
	v_mfma_f32_16x16x32_bf16 v[124:127], v[160:163], v[132:135], v[124:127]
	s_waitcnt lgkmcnt(2)
	v_mfma_f32_16x16x32_bf16 v[128:131], v[156:159], v[132:135], v[128:131]
	s_waitcnt lgkmcnt(0)
	v_mfma_f32_16x16x32_bf16 v[120:123], v[140:143], v[132:135], v[120:123]
	v_mfma_f32_16x16x32_bf16 v[100:103], v[144:147], v[136:139], v[100:103]
	v_mfma_f32_16x16x32_bf16 v[108:111], v[160:163], v[136:139], v[108:111]
	v_mfma_f32_16x16x32_bf16 v[112:115], v[156:159], v[136:139], v[112:115]
	v_mfma_f32_16x16x32_bf16 v[104:107], v[140:143], v[136:139], v[104:107]
	v_mfma_f32_16x16x32_bf16 v[84:87], v[144:147], v[148:151], v[84:87]
	v_mfma_f32_16x16x32_bf16 v[92:95], v[160:163], v[148:151], v[92:95]
	v_mfma_f32_16x16x32_bf16 v[96:99], v[156:159], v[148:151], v[96:99]
	v_mfma_f32_16x16x32_bf16 v[88:91], v[140:143], v[148:151], v[88:91]
	v_mfma_f32_16x16x32_bf16 v[68:71], v[144:147], v[152:155], v[68:71]
	v_mfma_f32_16x16x32_bf16 v[76:79], v[160:163], v[152:155], v[76:79]
	v_mfma_f32_16x16x32_bf16 v[80:83], v[156:159], v[152:155], v[80:83]
	v_mfma_f32_16x16x32_bf16 v[72:75], v[140:143], v[152:155], v[72:75]
	s_setprio 0
	s_cbranch_scc1 .LBB0_404
	s_mov_b32 s88, s36
	s_branch .LBB0_390

; #define LAS __attribute__((address_space(3)))
; template <bool ISA>
; __device__ __forceinline__ void attn_unit(LAS unsigned char* lds, const AttnArgs& T, int sc, int wave, int) {
;     ...
;             const unsigned voff = (unsigned)(((lane >> 3) * pitch + (((lane & 7) ^ ((lane >> 3) & 6)) * 8)) * 2);
; #pragma unroll
;             for (int i = 0; i < 8; ++i)
;                 __builtin_amdgcn_global_load_lds((const unsigned*)((const char*)(vp + (size_t)(8 * i) * pitch) + voff), (LAS unsigned*)(vst + i * 1024), 16, 0, 0);
;         }
;         bf16x8 pf[4][2];
; #pragma unroll
;         for (int qh = 0; qh < 2; ++qh) {
;             f32x4 s[4][2];
;             const LAS float* eb = ext + (768 + 32 * qh + fr - 64 * kc - 4 * fq);
; #pragma unroll
;             for (int kb = 0; kb < 4; ++kb)
; #pragma unroll
;                 for (int q2 = 0; q2 < 2; ++q2) {
;                     f32x4 c0 = (f32x4){0.f, 0.f, 0.f, 0.f};
;                     if (ISA) { const LAS float* e = eb + (16 * q2 - 16 * kb); c0 = (f32x4){e[0], e[-1], e[-2], e[-3]}; }
;                     f32x4 t = __builtin_amdgcn_mfma_f32_16x16x32_bf16(kf[kb][0], qf[2 * qh + q2][0], c0, 0, 0, 0);
;                     s[kb][q2] = __builtin_amdgcn_mfma_f32_16x16x32_bf16(kf[kb][1], qf[2 * qh + q2][1], t, 0, 0, 0);
;                 }
;             if (qh == 1) { const int kn = kc < NPREV ? kc + 1 : kc; const bf16 *kpn, *vpn; int pitchn; ATT_TILE_PTRS(kn, kpn, vpn, pitchn); (void)vpn; ATT_LOAD_K(kpn, pitchn); }
; #pragma unroll
;             for (int q2 = 0; q2 < 2; ++q2) {
;                 const int qb = 2 * qh + q2;
;                 float mx = fmaxf(fmaxf(s[0][q2][0], s[0][q2][1]), s[0][q2][2]);
;                 mx = fmaxf(fmaxf(mx, s[0][q2][3]), s[1][q2][0]); mx = fmaxf(fmaxf(mx, s[1][q2][1]), s[1][q2][2]); mx = fmaxf(fmaxf(mx, s[1][q2][3]), s[2][q2][0]);
;                 mx = fmaxf(fmaxf(mx, s[2][q2][1]), s[2][q2][2]); mx = fmaxf(fmaxf(mx, s[2][q2][3]), s[3][q2][0]); mx = fmaxf(fmaxf(mx, s[3][q2][1]), s[3][q2][2]); mx = fmaxf(mx, s[3][q2][3]);
;                 if (!__all(mx <= mrow[qb] + ATT_THR)) {
;                     mx = fmaxf(mx, __shfl_xor(mx, 16)); mx = fmaxf(mx, __shfl_xor(mx, 32));
;                     const float mnew = fmaxf(mrow[qb], mx), alpha = fexp2(mrow[qb] - mnew);
;                     mrow[qb] = mnew; lrow[qb] = lrow[qb] * alpha;
; #pragma unroll
.LBB0_1096:
	v_mul_lo_u32 v0, v202, s46
	v_or_b32_e32 v0, v0, v201
	s_mov_b32 m0, s92
	v_lshl_add_u64 v[2:3], s[44:45], 0, v[0:1]
	s_lshl_b32 s10, s46, 4
	global_load_lds_dwordx4 v0, s[44:45]
	v_lshl_add_u64 v[148:149], v[2:3], 0, s[10:11]
	s_mov_b32 m0, s95
	s_lshl_b32 s10, s46, 5
	global_load_lds_dwordx4 v[148:149], off
	v_lshl_add_u64 v[148:149], v[2:3], 0, s[10:11]
	s_mov_b32 m0, s96
	s_mul_i32 s10, s46, 48
	global_load_lds_dwordx4 v[148:149], off
	v_lshl_add_u64 v[152:153], v[2:3], 0, s[10:11]
	s_mov_b32 m0, s97
	s_lshl_b32 s10, s46, 6
	global_load_lds_dwordx4 v[152:153], off
	v_lshl_add_u64 v[152:153], v[2:3], 0, s[10:11]
	s_mov_b32 m0, s91
	s_mul_i32 s10, s46, 0x50
	global_load_lds_dwordx4 v[152:153], off
	v_lshl_add_u64 v[152:153], v[2:3], 0, s[10:11]
	s_mov_b32 m0, s72
	s_mul_i32 s10, s46, 0x60
	global_load_lds_dwordx4 v[152:153], off
	v_lshl_add_u64 v[152:153], v[2:3], 0, s[10:11]
	s_mov_b32 m0, s73
	s_mul_i32 s10, s46, 0x70
	global_load_lds_dwordx4 v[152:153], off
	v_lshl_add_u64 v[2:3], v[2:3], 0, s[10:11]
	s_mov_b32 m0, s4
	s_waitcnt vmcnt(7)
	s_setprio 1
	v_mfma_f32_16x16x32_bf16 v[132:135], v[64:67], v[4:7], 0
	global_load_lds_dwordx4 v[2:3], off
	v_mfma_f32_16x16x32_bf16 v[140:143], v[60:63], v[8:11], v[132:135]
	v_mfma_f32_16x16x32_bf16 v[132:135], v[64:67], v[12:15], 0
	v_mfma_f32_16x16x32_bf16 v[136:139], v[60:63], v[16:19], v[132:135]
	s_nop 5
	v_max_f32_e32 v0, v141, v141
	v_max_f32_e32 v2, v140, v140
	v_max_f32_e32 v0, v2, v0
	v_mfma_f32_16x16x32_bf16 v[132:135], v[56:59], v[4:7], 0
	v_max3_f32 v0, v0, v142, v143
	v_add_f32_e32 v2, 0x40c00000, v208
	v_mfma_f32_16x16x32_bf16 v[148:151], v[48:51], v[4:7], 0
	v_mfma_f32_16x16x32_bf16 v[132:135], v[52:55], v[8:11], v[132:135]
	v_mfma_f32_16x16x32_bf16 v[152:155], v[40:43], v[4:7], 0
	v_mfma_f32_16x16x32_bf16 v[156:159], v[44:47], v[8:11], v[148:151]
	s_nop 5
	v_max3_f32 v0, v0, v132, v133
	v_max3_f32 v0, v0, v134, v135
	v_mfma_f32_16x16x32_bf16 v[144:147], v[56:59], v[12:15], 0
	v_mfma_f32_16x16x32_bf16 v[148:151], v[48:51], v[12:15], 0
	v_max3_f32 v0, v0, v156, v157
	v_max3_f32 v0, v0, v158, v159
	v_mfma_f32_16x16x32_bf16 v[160:163], v[36:39], v[8:11], v[152:155]
	v_mfma_f32_16x16x32_bf16 v[152:155], v[40:43], v[12:15], 0
	v_mfma_f32_16x16x32_bf16 v[144:147], v[52:55], v[16:19], v[144:147]
	s_nop 5
	v_max3_f32 v0, v0, v160, v161
	v_max3_f32 v0, v0, v162, v163
	v_cmp_le_f32_e32 vcc, v0, v2
	v_mfma_f32_16x16x32_bf16 v[148:151], v[44:47], v[16:19], v[148:151]
	s_cmp_eq_u64 vcc, exec
	v_mfma_f32_16x16x32_bf16 v[152:155], v[36:39], v[16:19], v[152:155]
	s_setprio 0
	s_cbranch_scc1 .LBB0_1098
	ds_bpermute_b32 v2, v197, v0
	v_max_f32_e32 v0, v0, v0
	s_waitcnt lgkmcnt(0)
	v_max_f32_e32 v2, v2, v2
	v_max_f32_e32 v0, v0, v2
	ds_bpermute_b32 v2, v198, v0
	s_waitcnt lgkmcnt(0)
	v_max3_f32 v2, v208, v0, v2
	v_sub_f32_e32 v0, v208, v2
	v_exp_f32_e32 v0, v0
	v_mov_b32_e32 v208, v2
	v_mul_f32_e32 v207, v207, v0
	v_pk_mul_f32 v[118:119], v[118:119], v[0:1] op_sel_hi:[1,0]
	v_pk_mul_f32 v[116:117], v[116:117], v[0:1] op_sel_hi:[1,0]
	v_pk_mul_f32 v[122:123], v[122:123], v[0:1] op_sel_hi:[1,0]
	v_pk_mul_f32 v[120:121], v[120:121], v[0:1] op_sel_hi:[1,0]
	v_pk_mul_f32 v[130:131], v[130:131], v[0:1] op_sel_hi:[1,0]
	v_pk_mul_f32 v[128:129], v[128:129], v[0:1] op_sel_hi:[1,0]
	v_pk_mul_f32 v[126:127], v[126:127], v[0:1] op_sel_hi:[1,0]
	v_pk_mul_f32 v[124:125], v[124:125], v[0:1] op_sel_hi:[1,0]

; #define LAS __attribute__((address_space(3)))
; __device__ __forceinline__ unsigned cvt_pk(float lo, float hi) { unsigned r; asm("v_cvt_pk_bf16_f32 %0, %1, %2" : "=v"(r) : "v"(lo), "v"(hi)); return r; }
; __device__ __forceinline__ float fexp2(float x) { return __builtin_amdgcn_exp2f(x); }
; template <bool ISA>
; __device__ __forceinline__ void attn_unit(LAS unsigned char* lds, const AttnArgs& T, int sc, int wave, int) {
;     ...
;                 const float mcur = mrow[qb];
;                 float ps = 0.f; float p[4][4];
; #pragma unroll
;                 for (int kb = 0; kb < 4; ++kb)
; #pragma unroll
;                     for (int j = 0; j < 4; ++j) { p[kb][j] = fexp2(s[kb][q2][j] - mcur); ps += p[kb][j]; }
;                 lrow[qb] += ps;
; #pragma unroll
;                 for (int kp2 = 0; kp2 < 2; ++kp2) {
;                     v4u w; w.x = cvt_pk(p[2 * kp2][0], p[2 * kp2][1]); w.y = cvt_pk(p[2 * kp2][2], p[2 * kp2][3]);
;                     w.z = cvt_pk(p[2 * kp2 + 1][0], p[2 * kp2 + 1][1]); w.w = cvt_pk(p[2 * kp2 + 1][2], p[2 * kp2 + 1][3]);
;                     pf[qb][kp2] = __builtin_bit_cast(bf16x8, w);
;                 }
;             }
;         }
;         asm volatile("s_waitcnt vmcnt(8)" ::: "memory");
;         __builtin_amdgcn_wave_barrier();
;         const int tq = (lane & 15) >> 2, tp = lane & 3;
; #pragma unroll
;         for (int kp2 = 0; kp2 < 2; ++kp2) {
;             bf16x8 vf[4];
; #pragma unroll
;             for (int db = 0; db < 4; ++db) {
;                 const int r8 = 4 * (fq & 1) + tq;
;                 LAS unsigned char* a0 = vst + (4 * kp2 + (fq >> 1)) * 1024 + r8 * 128 + (((2 * db + (tp >> 1)) ^ (r8 & 6)) * 16) + (tp & 1) * 8;
;                 const s16x4 lo = __builtin_bit_cast(s16x4, __builtin_amdgcn_ds_read_tr16_b64_v4i16((LAS s16x4*)a0));
;                 const s16x4 hi = __builtin_bit_cast(s16x4, __builtin_amdgcn_ds_read_tr16_b64_v4i16((LAS s16x4*)(a0 + 2048)));
;                 vf[db] = (bf16x8){lo[0], lo[1], lo[2], lo[3], hi[0], hi[1], hi[2], hi[3]};
;             }
; #pragma unroll
;             for (int qb = 0; qb < 4; ++qb)
; #pragma unroll
;                 for (int db = 0; db < 4; ++db) o[db][qb] = __builtin_amdgcn_mfma_f32_16x16x32_bf16(vf[db], pf[qb][kp2], o[db][qb], 0, 0, 0);
;         }
.LBB0_1104:
	v_add_f32_e32 v0, 0, v0
	v_add_f32_e32 v0, v239, v0
	v_add_f32_e32 v0, v240, v0
	v_add_f32_e32 v0, v241, v0
	v_add_f32_e32 v0, v242, v0
	v_add_f32_e32 v0, v243, v0
	v_add_f32_e32 v0, v244, v0
	v_add_f32_e32 v0, v245, v0
	v_add_f32_e32 v0, v172, v0
	v_add_f32_e32 v0, v173, v0
	v_add_f32_e32 v0, v174, v0
	v_add_f32_e32 v0, v175, v0
	v_add_f32_e32 v0, v176, v0
	v_add_f32_e32 v0, v177, v0
	v_add_f32_e32 v0, v178, v0
	v_add_f32_e32 v0, v179, v0
	v_add_f32_e32 v187, v187, v0
	v_add_f32_e32 v0, 0, v223
	v_add_f32_e32 v0, v224, v0
	v_add_f32_e32 v0, v225, v0
	v_add_f32_e32 v0, v226, v0
	v_add_f32_e32 v0, v227, v0
	v_add_f32_e32 v0, v228, v0
	v_add_f32_e32 v0, v229, v0
	v_add_f32_e32 v0, v230, v0
	v_add_f32_e32 v0, v231, v0
	v_add_f32_e32 v0, v232, v0
	v_add_f32_e32 v0, v233, v0
	v_add_f32_e32 v0, v234, v0
	v_add_f32_e32 v0, v235, v0
	v_add_f32_e32 v0, v236, v0
	v_add_f32_e32 v0, v237, v0
	v_add_f32_e32 v0, v238, v0
	v_add_f32_e32 v189, v189, v0
	v_add_f32_e32 v0, 0, v2
	v_add_f32_e32 v0, v3, v0
	v_add_f32_e32 v0, v209, v0
	v_add_f32_e32 v0, v210, v0
	v_add_f32_e32 v0, v211, v0
	v_add_f32_e32 v0, v212, v0
	v_add_f32_e32 v0, v213, v0
	v_add_f32_e32 v0, v214, v0
	v_add_f32_e32 v0, v215, v0
	v_add_f32_e32 v0, v216, v0
	v_add_f32_e32 v0, v217, v0
	v_add_f32_e32 v0, v218, v0
	v_add_f32_e32 v0, v219, v0
	v_add_f32_e32 v0, v220, v0
	v_add_f32_e32 v0, v221, v0
	v_add_f32_e32 v0, v222, v0
	v_add_f32_e32 v207, v207, v0
	v_sub_f32_e32 v0, v152, v185
	v_exp_f32_e32 v0, v0
	v_sub_f32_e32 v3, v153, v185
	v_exp_f32_e32 v3, v3
	v_sub_f32_e32 v152, v154, v185
	v_exp_f32_e32 v152, v152
	v_sub_f32_e32 v153, v155, v185
	v_exp_f32_e32 v153, v153
	v_sub_f32_e32 v154, v160, v185
	v_add_f32_e32 v2, 0, v0
	v_exp_f32_e32 v154, v154
	v_sub_f32_e32 v155, v161, v185
	v_add_f32_e32 v2, v3, v2
	v_exp_f32_e32 v155, v155
	v_sub_f32_e32 v160, v162, v185
	v_add_f32_e32 v2, v152, v2
	v_exp_f32_e32 v172, v160
	v_sub_f32_e32 v160, v163, v185
	v_add_f32_e32 v2, v153, v2
	v_exp_f32_e32 v163, v160
	v_sub_f32_e32 v160, v168, v185
	v_add_f32_e32 v2, v154, v2
	v_exp_f32_e32 v168, v160
	v_sub_f32_e32 v160, v169, v185
	v_add_f32_e32 v2, v155, v2
	v_exp_f32_e32 v169, v160
	v_sub_f32_e32 v160, v170, v185
	v_add_f32_e32 v2, v172, v2
	v_exp_f32_e32 v170, v160
	v_sub_f32_e32 v160, v171, v185
	v_add_f32_e32 v2, v163, v2
	v_exp_f32_e32 v171, v160
	v_sub_f32_e32 v160, v164, v185
	v_add_f32_e32 v2, v168, v2
	v_exp_f32_e32 v164, v160
	v_sub_f32_e32 v160, v165, v185
	v_add_f32_e32 v2, v169, v2
	v_exp_f32_e32 v165, v160
	v_sub_f32_e32 v160, v166, v185
	v_add_f32_e32 v2, v170, v2
	v_exp_f32_e32 v166, v160
	v_sub_f32_e32 v160, v167, v185
	v_add_f32_e32 v2, v171, v2
	v_exp_f32_e32 v167, v160
	v_add_f32_e32 v2, v164, v2
	v_add_f32_e32 v2, v165, v2
	v_add_f32_e32 v2, v166, v2
	v_add_f32_e32 v2, v167, v2
	v_cvt_pk_bf16_f32 v161, v152, v153
	v_cvt_pk_bf16_f32 v162, v154, v155
	v_cvt_pk_bf16_f32 v163, v172, v163
	v_cvt_pk_bf16_f32 v152, v168, v169
	v_cvt_pk_bf16_f32 v153, v170, v171
	v_cvt_pk_bf16_f32 v154, v164, v165
	v_cvt_pk_bf16_f32 v155, v166, v167
	s_waitcnt vmcnt(8)
	ds_read_b64_tr_b16 v[164:165], v203
	ds_read_b64_tr_b16 v[166:167], v203 offset:2048
	ds_read_b64_tr_b16 v[168:169], v204
	ds_read_b64_tr_b16 v[170:171], v204 offset:2048
	ds_read_b64_tr_b16 v[172:173], v205
	ds_read_b64_tr_b16 v[174:175], v205 offset:2048
	ds_read_b64_tr_b16 v[176:177], v206
	ds_read_b64_tr_b16 v[178:179], v206 offset:2048
	v_cvt_pk_bf16_f32 v160, v0, v3
	s_waitcnt lgkmcnt(0)
	s_setprio 1
	v_mfma_f32_16x16x32_bf16 v[116:119], v[164:167], v[140:143], v[116:119]
	s_add_i32 s63, s63, 64
	v_add_f32_e32 v184, v184, v2
	s_cmp_gt_u32 s61, 1
	v_mfma_f32_16x16x32_bf16 v[120:123], v[168:171], v[140:143], v[120:123]
	v_mfma_f32_16x16x32_bf16 v[128:131], v[172:175], v[140:143], v[128:131]
	v_mfma_f32_16x16x32_bf16 v[124:127], v[176:179], v[140:143], v[124:127]
	v_mfma_f32_16x16x32_bf16 v[100:103], v[164:167], v[144:147], v[100:103]
	v_mfma_f32_16x16x32_bf16 v[104:107], v[168:171], v[144:147], v[104:107]
	v_mfma_f32_16x16x32_bf16 v[112:115], v[172:175], v[144:147], v[112:115]
	v_mfma_f32_16x16x32_bf16 v[108:111], v[176:179], v[144:147], v[108:111]
	v_mfma_f32_16x16x32_bf16 v[84:87], v[164:167], v[156:159], v[84:87]
	v_mfma_f32_16x16x32_bf16 v[88:91], v[168:171], v[156:159], v[88:91]
	v_mfma_f32_16x16x32_bf16 v[96:99], v[172:175], v[156:159], v[96:99]
	v_mfma_f32_16x16x32_bf16 v[92:95], v[176:179], v[156:159], v[92:95]
	v_mfma_f32_16x16x32_bf16 v[68:71], v[164:167], v[160:163], v[68:71]
	v_mfma_f32_16x16x32_bf16 v[72:75], v[168:171], v[160:163], v[72:75]
	v_mfma_f32_16x16x32_bf16 v[80:83], v[172:175], v[160:163], v[80:83]
	v_mfma_f32_16x16x32_bf16 v[76:79], v[176:179], v[160:163], v[76:79]
	ds_read_b64_tr_b16 v[144:145], v203 offset:4096
	ds_read_b64_tr_b16 v[146:147], v203 offset:6144
	ds_read_b64_tr_b16 v[160:161], v204 offset:4096
	ds_read_b64_tr_b16 v[162:163], v204 offset:6144
	ds_read_b64_tr_b16 v[156:157], v205 offset:4096
	ds_read_b64_tr_b16 v[158:159], v205 offset:6144
	ds_read_b64_tr_b16 v[140:141], v206 offset:4096
	ds_read_b64_tr_b16 v[142:143], v206 offset:6144
	s_waitcnt lgkmcnt(6)
	v_mfma_f32_16x16x32_bf16 v[116:119], v[144:147], v[132:135], v[116:119]
	s_waitcnt lgkmcnt(4)
	v_mfma_f32_16x16x32_bf16 v[120:123], v[160:163], v[132:135], v[120:123]
	s_waitcnt lgkmcnt(2)
	v_mfma_f32_16x16x32_bf16 v[128:131], v[156:159], v[132:135], v[128:131]
	s_waitcnt lgkmcnt(0)
	v_mfma_f32_16x16x32_bf16 v[124:127], v[140:143], v[132:135], v[124:127]
	v_mfma_f32_16x16x32_bf16 v[100:103], v[144:147], v[136:139], v[100:103]
	v_mfma_f32_16x16x32_bf16 v[104:107], v[160:163], v[136:139], v[104:107]
	v_mfma_f32_16x16x32_bf16 v[112:115], v[156:159], v[136:139], v[112:115]
	v_mfma_f32_16x16x32_bf16 v[108:111], v[140:143], v[136:139], v[108:111]
	v_mfma_f32_16x16x32_bf16 v[84:87], v[144:147], v[148:151], v[84:87]
	v_mfma_f32_16x16x32_bf16 v[88:91], v[160:163], v[148:151], v[88:91]
	v_mfma_f32_16x16x32_bf16 v[96:99], v[156:159], v[148:151], v[96:99]
	v_mfma_f32_16x16x32_bf16 v[92:95], v[140:143], v[148:151], v[92:95]
	v_mfma_f32_16x16x32_bf16 v[68:71], v[144:147], v[152:155], v[68:71]
	v_mfma_f32_16x16x32_bf16 v[72:75], v[160:163], v[152:155], v[72:75]
	v_mfma_f32_16x16x32_bf16 v[80:83], v[156:159], v[152:155], v[80:83]
	v_mfma_f32_16x16x32_bf16 v[76:79], v[140:143], v[152:155], v[76:79]
	s_setprio 0
	s_cbranch_scc1 .LBB0_1107
	s_mov_b32 s61, s44
	s_branch .LBB0_1092

; #define LAS __attribute__((address_space(3)))
; __device__ __forceinline__ unsigned cvt_pk(float lo, float hi) { unsigned r; asm("v_cvt_pk_bf16_f32 %0, %1, %2" : "=v"(r) : "v"(lo), "v"(hi)); return r; }
; __device__ __forceinline__ float fexp2(float x) { return __builtin_amdgcn_exp2f(x); }
; template <bool ISA>
; __device__ __forceinline__ void attn_unit(LAS unsigned char* lds, const AttnArgs& T, int sc, int wave, int) {
;     ...
;                 const float mcur = mrow[qb];
;                 float ps = 0.f; float p[4][4];
; #pragma unroll
;                 for (int kb = 0; kb < 4; ++kb)
; #pragma unroll
;                     for (int j = 0; j < 4; ++j) { p[kb][j] = fexp2(s[kb][q2][j] - mcur); ps += p[kb][j]; }
;                 lrow[qb] += ps;
; #pragma unroll
;                 for (int kp2 = 0; kp2 < 2; ++kp2) {
;                     v4u w; w.x = cvt_pk(p[2 * kp2][0], p[2 * kp2][1]); w.y = cvt_pk(p[2 * kp2][2], p[2 * kp2][3]);
;                     w.z = cvt_pk(p[2 * kp2 + 1][0], p[2 * kp2 + 1][1]); w.w = cvt_pk(p[2 * kp2 + 1][2], p[2 * kp2 + 1][3]);
;                     pf[qb][kp2] = __builtin_bit_cast(bf16x8, w);
;                 }
;             }
;         }
;         asm volatile("s_waitcnt vmcnt(8)" ::: "memory");
;         __builtin_amdgcn_wave_barrier();
;         const int tq = (lane & 15) >> 2, tp = lane & 3;
; #pragma unroll
;         for (int kp2 = 0; kp2 < 2; ++kp2) {
;             bf16x8 vf[4];
; #pragma unroll
;             for (int db = 0; db < 4; ++db) {
;                 const int r8 = 4 * (fq & 1) + tq;
;                 LAS unsigned char* a0 = vst + (4 * kp2 + (fq >> 1)) * 1024 + r8 * 128 + (((2 * db + (tp >> 1)) ^ (r8 & 6)) * 16) + (tp & 1) * 8;
;                 const s16x4 lo = __builtin_bit_cast(s16x4, __builtin_amdgcn_ds_read_tr16_b64_v4i16((LAS s16x4*)a0));
;                 const s16x4 hi = __builtin_bit_cast(s16x4, __builtin_amdgcn_ds_read_tr16_b64_v4i16((LAS s16x4*)(a0 + 2048)));
;                 vf[db] = (bf16x8){lo[0], lo[1], lo[2], lo[3], hi[0], hi[1], hi[2], hi[3]};
;             }
; #pragma unroll
;             for (int qb = 0; qb < 4; ++qb)
; #pragma unroll
;                 for (int db = 0; db < 4; ++db) o[db][qb] = __builtin_amdgcn_mfma_f32_16x16x32_bf16(vf[db], pf[qb][kp2], o[db][qb], 0, 0, 0);
;         }
.LBB0_1138:
	v_add_f32_e32 v0, 0, v0
	v_add_f32_e32 v0, v235, v0
	v_add_f32_e32 v0, v236, v0
	v_add_f32_e32 v0, v237, v0
	v_add_f32_e32 v0, v148, v0
	v_add_f32_e32 v0, v149, v0
	v_add_f32_e32 v0, v150, v0
	v_add_f32_e32 v0, v151, v0
	v_add_f32_e32 v0, v238, v0
	v_add_f32_e32 v0, v239, v0
	v_add_f32_e32 v0, v240, v0
	v_add_f32_e32 v0, v241, v0
	v_add_f32_e32 v0, v160, v0
	v_add_f32_e32 v0, v161, v0
	v_add_f32_e32 v0, v162, v0
	v_add_f32_e32 v0, v163, v0
	v_add_f32_e32 v207, v207, v0
	v_add_f32_e32 v0, 0, v2
	v_add_f32_e32 v0, v3, v0
	v_add_f32_e32 v0, v221, v0
	v_add_f32_e32 v0, v222, v0
	v_add_f32_e32 v0, v223, v0
	v_add_f32_e32 v0, v224, v0
	v_add_f32_e32 v0, v225, v0
	v_add_f32_e32 v0, v226, v0
	v_add_f32_e32 v0, v227, v0
	v_add_f32_e32 v0, v228, v0
	v_add_f32_e32 v0, v229, v0
	v_add_f32_e32 v0, v230, v0
	v_add_f32_e32 v0, v231, v0
	v_add_f32_e32 v0, v232, v0
	v_add_f32_e32 v0, v233, v0
	v_add_f32_e32 v0, v234, v0
	v_add_f32_e32 v216, v216, v0
	v_sub_f32_e32 v0, v168, v217
	v_exp_f32_e32 v0, v0
	v_sub_f32_e32 v3, v169, v217
	v_exp_f32_e32 v3, v3
	v_sub_f32_e32 v148, v170, v217
	v_exp_f32_e32 v148, v148
	v_sub_f32_e32 v149, v171, v217
	v_exp_f32_e32 v149, v149
	v_sub_f32_e32 v150, v164, v217
	v_add_f32_e32 v2, 0, v0
	v_exp_f32_e32 v150, v150
	v_sub_f32_e32 v151, v165, v217
	v_add_f32_e32 v2, v3, v2
	v_exp_f32_e32 v151, v151
	v_sub_f32_e32 v160, v166, v217
	v_add_f32_e32 v2, v148, v2
	v_exp_f32_e32 v163, v160
	v_sub_f32_e32 v160, v167, v217
	v_add_f32_e32 v2, v149, v2
	v_exp_f32_e32 v164, v160
	v_sub_f32_e32 v160, v172, v217
	v_add_f32_e32 v2, v150, v2
	v_exp_f32_e32 v165, v160
	v_sub_f32_e32 v160, v173, v217
	v_add_f32_e32 v2, v151, v2
	v_exp_f32_e32 v166, v160
	v_sub_f32_e32 v160, v174, v217
	v_add_f32_e32 v2, v163, v2
	v_exp_f32_e32 v167, v160
	v_sub_f32_e32 v160, v175, v217
	v_add_f32_e32 v2, v164, v2
	v_exp_f32_e32 v168, v160
	v_sub_f32_e32 v160, v176, v217
	v_add_f32_e32 v2, v165, v2
	v_exp_f32_e32 v169, v160
	v_sub_f32_e32 v160, v177, v217
	v_add_f32_e32 v2, v166, v2
	v_exp_f32_e32 v170, v160
	v_sub_f32_e32 v160, v178, v217
	v_add_f32_e32 v2, v167, v2
	v_exp_f32_e32 v171, v160
	v_sub_f32_e32 v160, v179, v217
	v_add_f32_e32 v2, v168, v2
	v_exp_f32_e32 v172, v160
	v_add_f32_e32 v180, 0, v180
	v_add_f32_e32 v2, v169, v2
	v_add_f32_e32 v180, v181, v180
	v_add_f32_e32 v2, v170, v2
	v_add_f32_e32 v180, v182, v180
	v_add_f32_e32 v2, v171, v2
	v_add_f32_e32 v180, v183, v180
	v_add_f32_e32 v2, v172, v2
	v_cvt_pk_bf16_f32 v161, v148, v149
	v_cvt_pk_bf16_f32 v162, v150, v151
	v_cvt_pk_bf16_f32 v163, v163, v164
	v_cvt_pk_bf16_f32 v148, v165, v166
	v_cvt_pk_bf16_f32 v149, v167, v168
	v_cvt_pk_bf16_f32 v150, v169, v170
	v_cvt_pk_bf16_f32 v151, v171, v172
	s_waitcnt vmcnt(8)
	ds_read_b64_tr_b16 v[164:165], v212
	ds_read_b64_tr_b16 v[166:167], v212 offset:2048
	ds_read_b64_tr_b16 v[168:169], v213
	ds_read_b64_tr_b16 v[170:171], v213 offset:2048
	ds_read_b64_tr_b16 v[172:173], v214
	ds_read_b64_tr_b16 v[174:175], v214 offset:2048
	ds_read_b64_tr_b16 v[176:177], v215
	ds_read_b64_tr_b16 v[178:179], v215 offset:2048
	v_add_f32_e32 v180, v184, v180
	v_add_f32_e32 v180, v185, v180
	v_add_f32_e32 v180, v186, v180
	v_add_f32_e32 v180, v187, v180
	v_cvt_pk_bf16_f32 v160, v0, v3
	v_add_f32_e32 v180, v188, v180
	s_waitcnt lgkmcnt(6)
	s_setprio 1
	v_mfma_f32_16x16x32_bf16 v[116:119], v[164:167], v[144:147], v[116:119]
	v_add_f32_e32 v180, v189, v180
	v_add_f32_e32 v180, v190, v180
	v_add_f32_e32 v180, v191, v180
	s_waitcnt lgkmcnt(4)
	v_mfma_f32_16x16x32_bf16 v[124:127], v[168:171], v[144:147], v[124:127]
	v_add_f32_e32 v180, v242, v180
	v_add_f32_e32 v180, v243, v180
	v_add_f32_e32 v180, v244, v180
	s_waitcnt lgkmcnt(2)
	v_mfma_f32_16x16x32_bf16 v[128:131], v[172:175], v[144:147], v[128:131]
	v_add_f32_e32 v180, v245, v180
	s_addk_i32 s66, 0xff00
	s_add_i32 s65, s65, 64
	s_waitcnt lgkmcnt(0)
	v_mfma_f32_16x16x32_bf16 v[120:123], v[176:179], v[144:147], v[120:123]
	s_add_i32 s42, s42, 64
	v_add_f32_e32 v206, v206, v180
	v_add_f32_e32 v204, v204, v2
	v_mfma_f32_16x16x32_bf16 v[100:103], v[164:167], v[152:155], v[100:103]
	s_cmp_gt_u32 s61, 7
	v_mfma_f32_16x16x32_bf16 v[108:111], v[168:171], v[152:155], v[108:111]
	v_mfma_f32_16x16x32_bf16 v[112:115], v[172:175], v[152:155], v[112:115]
	v_mfma_f32_16x16x32_bf16 v[104:107], v[176:179], v[152:155], v[104:107]
	v_mfma_f32_16x16x32_bf16 v[84:87], v[164:167], v[156:159], v[84:87]
	v_mfma_f32_16x16x32_bf16 v[92:95], v[168:171], v[156:159], v[92:95]
	v_mfma_f32_16x16x32_bf16 v[96:99], v[172:175], v[156:159], v[96:99]
	v_mfma_f32_16x16x32_bf16 v[88:91], v[176:179], v[156:159], v[88:91]
	v_mfma_f32_16x16x32_bf16 v[68:71], v[164:167], v[160:163], v[68:71]
	v_mfma_f32_16x16x32_bf16 v[76:79], v[168:171], v[160:163], v[76:79]
	v_mfma_f32_16x16x32_bf16 v[80:83], v[172:175], v[160:163], v[80:83]
	v_mfma_f32_16x16x32_bf16 v[72:75], v[176:179], v[160:163], v[72:75]
	ds_read_b64_tr_b16 v[152:153], v212 offset:4096
	ds_read_b64_tr_b16 v[154:155], v212 offset:6144
	ds_read_b64_tr_b16 v[160:161], v213 offset:4096
	ds_read_b64_tr_b16 v[162:163], v213 offset:6144
	ds_read_b64_tr_b16 v[156:157], v214 offset:4096
	ds_read_b64_tr_b16 v[158:159], v214 offset:6144
	ds_read_b64_tr_b16 v[144:145], v215 offset:4096
	ds_read_b64_tr_b16 v[146:147], v215 offset:6144
	s_waitcnt lgkmcnt(6)
	v_mfma_f32_16x16x32_bf16 v[116:119], v[152:155], v[132:135], v[116:119]
	s_waitcnt lgkmcnt(4)
	v_mfma_f32_16x16x32_bf16 v[124:127], v[160:163], v[132:135], v[124:127]
	s_waitcnt lgkmcnt(2)
	v_mfma_f32_16x16x32_bf16 v[128:131], v[156:159], v[132:135], v[128:131]
	s_waitcnt lgkmcnt(0)
	v_mfma_f32_16x16x32_bf16 v[120:123], v[144:147], v[132:135], v[120:123]
	v_mfma_f32_16x16x32_bf16 v[100:103], v[152:155], v[136:139], v[100:103]
	v_mfma_f32_16x16x32_bf16 v[108:111], v[160:163], v[136:139], v[108:111]
	v_mfma_f32_16x16x32_bf16 v[112:115], v[156:159], v[136:139], v[112:115]
	v_mfma_f32_16x16x32_bf16 v[104:107], v[144:147], v[136:139], v[104:107]
	v_mfma_f32_16x16x32_bf16 v[84:87], v[152:155], v[140:143], v[84:87]
	v_mfma_f32_16x16x32_bf16 v[92:95], v[160:163], v[140:143], v[92:95]
	v_mfma_f32_16x16x32_bf16 v[96:99], v[156:159], v[140:143], v[96:99]
	v_mfma_f32_16x16x32_bf16 v[88:91], v[144:147], v[140:143], v[88:91]
	v_mfma_f32_16x16x32_bf16 v[68:71], v[152:155], v[148:151], v[68:71]
	v_mfma_f32_16x16x32_bf16 v[76:79], v[160:163], v[148:151], v[76:79]
	v_mfma_f32_16x16x32_bf16 v[80:83], v[156:159], v[148:151], v[80:83]
	v_mfma_f32_16x16x32_bf16 v[72:75], v[144:147], v[148:151], v[72:75]
	s_setprio 0
	s_cbranch_scc1 .LBB0_1140
	s_mov_b32 s61, s43
	s_branch .LBB0_1126
